# G1A: head-norm tiles balanced to three per workgroup (column block rotated in the second row group) and the hand-written lighter head-norm epilogue
# speedup vs baseline: 1.0019x; 1.0019x over previous
;     __device__ bool next(int i, pg8::Unit& u) const { const int L = i * G + c; if (L >= 1280) return false; u.pn = L >> 6; u.pm = (L & 63) + (u.pn >= 16 ? 64 : 0); return true; }
;     __host__ __device__ bool next(int i, Unit& u) const {
;         const long L = (long)i * G + c; if (L >= nwg) return false;
;         int wgid = (int)L; { const int q = nwg / NXCD, r = nwg % NXCD, xcd = wgid % NXCD, off = wgid / NXCD; wgid = (xcd < r ? xcd * (q + 1) : r * (q + 1) + (xcd - r) * q) + off; }
;         const int nig = WGM * nN, gid = wgid / nig, fm = gid * WGM, gsz = (nM - fm) < WGM ? (nM - fm) : WGM;
;         u.pm = fm + ((wgid % nig) % gsz); u.pn = (wgid % nig) / gsz; return true;
;     }
.LBB0_12:
	s_add_i32 s52, s52, 1
	s_mul_i32 s0, s52, s59
	s_mul_hi_u32 s1, s52, s48
	s_add_i32 s1, s1, s0
	s_mul_i32 s0, s52, s48
	v_readlane_b32 s2, v231, 0
	s_add_u32 s2, s0, s2
	s_addc_u32 s3, s1, s42
	v_cmp_ge_i64_e32 vcc, s[2:3], v[144:145]
	v_cmp_lt_i64_e64 s[4:5], s[2:3], v[144:145]
	s_cbranch_vccnz .LBB0_14
	s_and_b32 s0, s2, 7
	s_lshr_b32 s1, s2, 3
	s_mul_i32 s0, s0, 0x100
	s_add_i32 s0, s0, s1
	s_lshr_b32 s1, s0, 7
	s_and_b32 s0, s0, 0x7f
	s_lshr_b32 s65, s0, 2
	s_lshr_b32 s3, s0, 5
	s_cmp_eq_u32 s3, 1
	s_cselect_b32 s3, 4, 0
	s_bitcmp1_b32 s1, 0
	s_cselect_b32 s3, s3, 0
	s_xor_b32 s65, s65, s3
	s_and_b32 s0, s0, 3
	s_lshl_b32 s1, s1, 2
	s_add_i32 s66, s0, s1
